# exchange acquire: dropped the L1 invalidate after the row-statistics counter wait (slots are stored and loaded sc1); keeps v10 residual prefetch
# speedup vs baseline: 1.0158x; 1.0158x over previous
;     __device__ __forceinline__ bool run(const f32x4 (&v)[2][2][4][2], const Unit& u, int wr, int wc, int fr, int fq, PG8_LAS unsigned char* lds, int wid, int lane) const {
;     ...
;             __builtin_amdgcn_fence(__ATOMIC_ACQUIRE, "agent");
;             if (lane == 0) flag[0] = dead ? 1u : 0u;
.LBB0_229:
	s_waitcnt vmcnt(0)
	s_nop 0
	s_and_b64 exec, exec, s[4:5]
	v_cndmask_b32_e64 v136, 0, 1, s[8:9]
	v_mov_b32_e32 v137, 0
	ds_write_b32 v137, v136 offset:10240

; __device__ __forceinline__ void thin_gemm_ln(const bf16* A, const bf16* Bt, int K, const float* base, float s, const float* g, const float* b, float* outf, bf16* outb, ...
;     ...
;         __builtin_amdgcn_fence(__ATOMIC_ACQUIRE, "agent");
;         if (lane == 0) flag[0] = dead ? 1u : 0u; }
.LBB0_260:
	s_waitcnt vmcnt(0)
	s_nop 0
	s_and_b64 exec, exec, s[0:1]
	s_add_i32 s0, 0, 0x23f88
	v_cndmask_b32_e64 v3, 0, 1, s[4:5]
	v_mov_b32_e32 v12, s0
	ds_write_b32 v12, v3

;     __device__ __forceinline__ bool run(const f32x4 (&v)[2][2][4][2], const Unit& u, int wr, int wc, int fr, int fq, PG8_LAS unsigned char* lds, int wid, int lane) const {
;     ...
;             __builtin_amdgcn_fence(__ATOMIC_ACQUIRE, "agent");
;             if (lane == 0) flag[0] = dead ? 1u : 0u;
.LBB0_1531:
	s_waitcnt vmcnt(0)
	s_nop 0
	s_and_b64 exec, exec, s[6:7]
	v_cndmask_b32_e64 v134, 0, 1, s[12:13]
	v_mov_b32_e32 v135, 0
	ds_write_b32 v135, v134 offset:10240

; __device__ __forceinline__ void thin_gemm_ln(const bf16* A, const bf16* Bt, int K, const float* base, float s, const float* g, const float* b, float* outf, bf16* outb, ...
;     ...
;         __builtin_amdgcn_fence(__ATOMIC_ACQUIRE, "agent");
;         if (lane == 0) flag[0] = dead ? 1u : 0u; }
.LBB0_1556:
	s_waitcnt vmcnt(0)
	s_nop 0
	s_and_b64 exec, exec, s[0:1]
	s_add_i32 s0, 0, 0x23f88
	v_cndmask_b32_e64 v3, 0, 1, s[6:7]
	v_mov_b32_e32 v12, s0
	ds_write_b32 v12, v3

;     __device__ __forceinline__ bool run(const f32x4 (&v)[2][2][4][2], const Unit& u, int wr, int wc, int fr, int fq, PG8_LAS unsigned char* lds, int wid, int lane) const {
;     ...
;             __builtin_amdgcn_fence(__ATOMIC_ACQUIRE, "agent");
;             if (lane == 0) flag[0] = dead ? 1u : 0u;
.LBB0_1748:
	s_waitcnt vmcnt(0)
	s_nop 0
	s_and_b64 exec, exec, s[4:5]
	v_cndmask_b32_e64 v134, 0, 1, s[10:11]
	v_mov_b32_e32 v135, 0
	ds_write_b32 v135, v134 offset:10240

; __device__ __forceinline__ void thin_gemm_ln(const bf16* A, const bf16* Bt, int K, const float* base, float s, const float* g, const float* b, float* outf, bf16* outb, ...
;     ...
;         __builtin_amdgcn_fence(__ATOMIC_ACQUIRE, "agent");
;         if (lane == 0) flag[0] = dead ? 1u : 0u; }
.LBB0_1779:
	s_waitcnt vmcnt(0)
	s_nop 0
	s_and_b64 exec, exec, s[0:1]
	s_add_i32 s0, 0, 0x23f88
	v_cndmask_b32_e64 v3, 0, 1, s[6:7]
	v_mov_b32_e32 v10, s0
	ds_write_b32 v10, v3
